# static s_setprio 1 for waves 4-7 before each K loop, per-phase flips removed (P1,P7,P13,P14 super-phase loops)
# baseline (speedup 1.0000x reference)
.LBB0_189:
	s_add_u32 s66, s66, 0x100
	s_addc_u32 s67, s67, 0
	s_add_u32 s64, s64, 0x40080
	v_mov_b32_e32 v2, 0
	s_addc_u32 s65, s65, 0
	s_mov_b32 s68, -2
	v_mov_b32_e32 v3, 0
	v_pk_mov_b32 v[4:5], v[2:3], v[2:3]
	v_pk_mov_b32 v[6:7], v[2:3], v[2:3]
	v_pk_mov_b32 v[8:9], v[2:3], v[2:3]
	v_pk_mov_b32 v[10:11], v[2:3], v[2:3]
	v_pk_mov_b32 v[12:13], v[2:3], v[2:3]
	v_pk_mov_b32 v[14:15], v[2:3], v[2:3]
	v_pk_mov_b32 v[16:17], v[2:3], v[2:3]
	v_pk_mov_b32 v[18:19], v[2:3], v[2:3]
	v_pk_mov_b32 v[20:21], v[2:3], v[2:3]
	v_pk_mov_b32 v[22:23], v[2:3], v[2:3]
	v_pk_mov_b32 v[24:25], v[2:3], v[2:3]
	v_pk_mov_b32 v[26:27], v[2:3], v[2:3]
	v_pk_mov_b32 v[28:29], v[2:3], v[2:3]
	v_pk_mov_b32 v[30:31], v[2:3], v[2:3]
	v_pk_mov_b32 v[32:33], v[2:3], v[2:3]
	v_pk_mov_b32 v[34:35], v[2:3], v[2:3]
	v_pk_mov_b32 v[36:37], v[2:3], v[2:3]
	v_pk_mov_b32 v[38:39], v[2:3], v[2:3]
	v_pk_mov_b32 v[40:41], v[2:3], v[2:3]
	v_pk_mov_b32 v[42:43], v[2:3], v[2:3]
	v_pk_mov_b32 v[44:45], v[2:3], v[2:3]
	v_pk_mov_b32 v[46:47], v[2:3], v[2:3]
	v_pk_mov_b32 v[48:49], v[2:3], v[2:3]
	v_pk_mov_b32 v[50:51], v[2:3], v[2:3]
	v_pk_mov_b32 v[52:53], v[2:3], v[2:3]
	v_pk_mov_b32 v[54:55], v[2:3], v[2:3]
	v_pk_mov_b32 v[56:57], v[2:3], v[2:3]
	v_pk_mov_b32 v[58:59], v[2:3], v[2:3]
	v_pk_mov_b32 v[60:61], v[2:3], v[2:3]
	v_pk_mov_b32 v[62:63], v[2:3], v[2:3]
	v_pk_mov_b32 v[64:65], v[2:3], v[2:3]
	v_pk_mov_b32 v[66:67], v[2:3], v[2:3]
	v_pk_mov_b32 v[68:69], v[2:3], v[2:3]
	v_pk_mov_b32 v[70:71], v[2:3], v[2:3]
	v_pk_mov_b32 v[72:73], v[2:3], v[2:3]
	v_pk_mov_b32 v[74:75], v[2:3], v[2:3]
	v_pk_mov_b32 v[76:77], v[2:3], v[2:3]
	v_pk_mov_b32 v[78:79], v[2:3], v[2:3]
	v_pk_mov_b32 v[80:81], v[2:3], v[2:3]
	v_pk_mov_b32 v[82:83], v[2:3], v[2:3]
	v_pk_mov_b32 v[84:85], v[2:3], v[2:3]
	v_pk_mov_b32 v[86:87], v[2:3], v[2:3]
	v_pk_mov_b32 v[88:89], v[2:3], v[2:3]
	v_pk_mov_b32 v[90:91], v[2:3], v[2:3]
	v_pk_mov_b32 v[92:93], v[2:3], v[2:3]
	v_pk_mov_b32 v[94:95], v[2:3], v[2:3]
	v_pk_mov_b32 v[96:97], v[2:3], v[2:3]
	v_pk_mov_b32 v[98:99], v[2:3], v[2:3]
	v_pk_mov_b32 v[100:101], v[2:3], v[2:3]
	v_pk_mov_b32 v[102:103], v[2:3], v[2:3]
	v_pk_mov_b32 v[104:105], v[2:3], v[2:3]
	v_pk_mov_b32 v[106:107], v[2:3], v[2:3]
	v_pk_mov_b32 v[108:109], v[2:3], v[2:3]
	v_pk_mov_b32 v[110:111], v[2:3], v[2:3]
	v_pk_mov_b32 v[112:113], v[2:3], v[2:3]
	v_pk_mov_b32 v[114:115], v[2:3], v[2:3]
	v_pk_mov_b32 v[116:117], v[2:3], v[2:3]
	v_pk_mov_b32 v[118:119], v[2:3], v[2:3]
	v_pk_mov_b32 v[120:121], v[2:3], v[2:3]
	v_pk_mov_b32 v[122:123], v[2:3], v[2:3]
	v_pk_mov_b32 v[124:125], v[2:3], v[2:3]
	v_pk_mov_b32 v[126:127], v[2:3], v[2:3]
	v_pk_mov_b32 v[128:129], v[2:3], v[2:3]
	v_readfirstlane_b32 s100, v0
	s_bitcmp1_b32 s100, 8
	s_cbranch_scc0 .Lsp_p1
	s_setprio 1
.Lsp_p1:
.LBB0_190:
	ds_read_b128 v[130:133], v155
	ds_read_b128 v[134:137], v155 offset:1024
	ds_read_b128 v[148:151], v155 offset:2048
	ds_read_b128 v[158:161], v155 offset:3072
	ds_read_b128 v[194:197], v157
	ds_read_b128 v[198:201], v157 offset:1024
	ds_read_b128 v[202:205], v157 offset:2048
	ds_read_b128 v[206:209], v157 offset:3072
	s_add_u32 s0, s64, 0xfffc0080
	s_addc_u32 s1, s65, -1
	s_cmp_eq_u32 s68, 12
	s_cselect_b32 s1, s11, s1
	s_cselect_b32 s0, s10, s0
	s_cselect_b32 s31, s63, s67
	s_cselect_b32 s30, s62, s66
	v_lshl_add_u64 v[252:253], s[64:65], 0, v[142:143]
	s_add_i32 m0, s7, 0xc000
	ds_read_b128 v[162:165], v156
	ds_read_b128 v[166:169], v156 offset:1024
	ds_read_b128 v[170:173], v156 offset:2048
	ds_read_b128 v[174:177], v156 offset:3072
	ds_read_b128 v[178:181], v156 offset:4096
	ds_read_b128 v[182:185], v156 offset:5120
	ds_read_b128 v[186:189], v156 offset:6144
	ds_read_b128 v[190:193], v156 offset:7168
	global_load_lds_dwordx4 v[252:253], off
	v_lshl_add_u64 v[252:253], v[252:253], 0, s[14:15]
	s_add_i32 m0, s7, 0xe000
	s_nop 0
	global_load_lds_dwordx4 v[252:253], off
	s_cmp_lg_u32 s98, 0
	s_cbranch_scc1 .Lsk1_p1
	s_waitcnt vmcnt(8)

.Lsk3_p1:
	s_waitcnt lgkmcnt(0)
	s_barrier
	v_mfma_f32_16x16x32_bf16 v[94:97], v[130:133], v[162:165], v[94:97]
	v_mfma_f32_16x16x32_bf16 v[90:93], v[148:151], v[162:165], v[90:93]
	v_mfma_f32_16x16x32_bf16 v[86:89], v[130:133], v[170:173], v[86:89]
	v_mfma_f32_16x16x32_bf16 v[82:85], v[148:151], v[170:173], v[82:85]
	v_mfma_f32_16x16x32_bf16 v[78:81], v[130:133], v[178:181], v[78:81]
	v_mfma_f32_16x16x32_bf16 v[74:77], v[148:151], v[178:181], v[74:77]
	v_mfma_f32_16x16x32_bf16 v[70:73], v[130:133], v[186:189], v[70:73]
	v_mfma_f32_16x16x32_bf16 v[66:69], v[148:151], v[186:189], v[66:69]
	v_mfma_f32_16x16x32_bf16 v[94:97], v[134:137], v[166:169], v[94:97]
	v_mfma_f32_16x16x32_bf16 v[90:93], v[158:161], v[166:169], v[90:93]
	v_mfma_f32_16x16x32_bf16 v[86:89], v[134:137], v[174:177], v[86:89]
	v_mfma_f32_16x16x32_bf16 v[82:85], v[158:161], v[174:177], v[82:85]
	v_mfma_f32_16x16x32_bf16 v[78:81], v[134:137], v[182:185], v[78:81]
	v_mfma_f32_16x16x32_bf16 v[74:77], v[158:161], v[182:185], v[74:77]
	v_mfma_f32_16x16x32_bf16 v[70:73], v[134:137], v[190:193], v[70:73]
	v_mfma_f32_16x16x32_bf16 v[66:69], v[158:161], v[190:193], v[66:69]
	v_mfma_f32_16x16x32_bf16 v[30:33], v[194:197], v[162:165], v[30:33]
	v_mfma_f32_16x16x32_bf16 v[26:29], v[202:205], v[162:165], v[26:29]
	v_mfma_f32_16x16x32_bf16 v[22:25], v[194:197], v[170:173], v[22:25]
	v_mfma_f32_16x16x32_bf16 v[18:21], v[202:205], v[170:173], v[18:21]
	v_mfma_f32_16x16x32_bf16 v[14:17], v[194:197], v[178:181], v[14:17]
	v_mfma_f32_16x16x32_bf16 v[10:13], v[202:205], v[178:181], v[10:13]
	v_mfma_f32_16x16x32_bf16 v[6:9], v[194:197], v[186:189], v[6:9]
	v_mfma_f32_16x16x32_bf16 v[2:5], v[202:205], v[186:189], v[2:5]
	v_mfma_f32_16x16x32_bf16 v[30:33], v[198:201], v[166:169], v[30:33]
	v_mfma_f32_16x16x32_bf16 v[26:29], v[206:209], v[166:169], v[26:29]
	v_mfma_f32_16x16x32_bf16 v[22:25], v[198:201], v[174:177], v[22:25]
	v_mfma_f32_16x16x32_bf16 v[18:21], v[206:209], v[174:177], v[18:21]
	v_mfma_f32_16x16x32_bf16 v[14:17], v[198:201], v[182:185], v[14:17]
	v_mfma_f32_16x16x32_bf16 v[10:13], v[206:209], v[182:185], v[10:13]
	v_mfma_f32_16x16x32_bf16 v[6:9], v[198:201], v[190:193], v[6:9]
	v_mfma_f32_16x16x32_bf16 v[2:5], v[206:209], v[190:193], v[2:5]
	s_add_i32 s0, 0, 0x18000
	v_add_u32_e32 v158, s0, v154
	s_barrier
	s_add_i32 s1, 0, 0x1c000
	v_add_u32_e32 v206, s1, v154
	ds_read_b128 v[130:133], v158
	ds_read_b128 v[134:137], v158 offset:1024
	ds_read_b128 v[148:151], v158 offset:2048
	ds_read_b128 v[158:161], v158 offset:3072
	ds_read_b128 v[194:197], v206
	ds_read_b128 v[198:201], v206 offset:1024
	ds_read_b128 v[202:205], v206 offset:2048
	ds_read_b128 v[206:209], v206 offset:3072
	s_mov_b32 m0, s25
	v_lshl_add_u64 v[252:253], v[212:213], 0, s[16:17]
	ds_read_b128 v[162:165], v156 offset:32768
	ds_read_b128 v[166:169], v156 offset:33792
	ds_read_b128 v[170:173], v156 offset:34816
	ds_read_b128 v[174:177], v156 offset:35840
	ds_read_b128 v[178:181], v156 offset:36864
	ds_read_b128 v[182:185], v156 offset:37888
	ds_read_b128 v[186:189], v156 offset:38912
	ds_read_b128 v[190:193], v156 offset:39936
	global_load_lds_dwordx4 v[252:253], off
	v_lshl_add_u64 v[252:253], v[212:213], 0, s[18:19]
	s_mov_b32 m0, s26
	s_nop 0
	global_load_lds_dwordx4 v[252:253], off
	s_waitcnt vmcnt(8)
	s_waitcnt lgkmcnt(0)
	s_barrier
	v_mfma_f32_16x16x32_bf16 v[126:129], v[130:133], v[162:165], v[126:129]
	v_mfma_f32_16x16x32_bf16 v[122:125], v[148:151], v[162:165], v[122:125]
	v_mfma_f32_16x16x32_bf16 v[118:121], v[130:133], v[170:173], v[118:121]
	v_mfma_f32_16x16x32_bf16 v[114:117], v[148:151], v[170:173], v[114:117]
	v_mfma_f32_16x16x32_bf16 v[110:113], v[130:133], v[178:181], v[110:113]
	v_mfma_f32_16x16x32_bf16 v[106:109], v[148:151], v[178:181], v[106:109]
	v_mfma_f32_16x16x32_bf16 v[102:105], v[130:133], v[186:189], v[102:105]
	v_mfma_f32_16x16x32_bf16 v[98:101], v[148:151], v[186:189], v[98:101]
	v_mfma_f32_16x16x32_bf16 v[126:129], v[134:137], v[166:169], v[126:129]
	v_mfma_f32_16x16x32_bf16 v[122:125], v[158:161], v[166:169], v[122:125]
	v_mfma_f32_16x16x32_bf16 v[118:121], v[134:137], v[174:177], v[118:121]
	v_mfma_f32_16x16x32_bf16 v[114:117], v[158:161], v[174:177], v[114:117]
	v_mfma_f32_16x16x32_bf16 v[110:113], v[134:137], v[182:185], v[110:113]
	v_mfma_f32_16x16x32_bf16 v[106:109], v[158:161], v[182:185], v[106:109]
	v_mfma_f32_16x16x32_bf16 v[102:105], v[134:137], v[190:193], v[102:105]
	v_mfma_f32_16x16x32_bf16 v[98:101], v[158:161], v[190:193], v[98:101]
	v_mfma_f32_16x16x32_bf16 v[62:65], v[194:197], v[162:165], v[62:65]
	v_mfma_f32_16x16x32_bf16 v[58:61], v[202:205], v[162:165], v[58:61]
	v_mfma_f32_16x16x32_bf16 v[54:57], v[194:197], v[170:173], v[54:57]
	v_mfma_f32_16x16x32_bf16 v[50:53], v[202:205], v[170:173], v[50:53]
	v_mfma_f32_16x16x32_bf16 v[46:49], v[194:197], v[178:181], v[46:49]
	v_mfma_f32_16x16x32_bf16 v[42:45], v[202:205], v[178:181], v[42:45]
	v_mfma_f32_16x16x32_bf16 v[38:41], v[194:197], v[186:189], v[38:41]
	v_mfma_f32_16x16x32_bf16 v[34:37], v[202:205], v[186:189], v[34:37]
	v_mfma_f32_16x16x32_bf16 v[62:65], v[198:201], v[166:169], v[62:65]
	v_mfma_f32_16x16x32_bf16 v[58:61], v[206:209], v[166:169], v[58:61]
	v_mfma_f32_16x16x32_bf16 v[54:57], v[198:201], v[174:177], v[54:57]
	v_mfma_f32_16x16x32_bf16 v[50:53], v[206:209], v[174:177], v[50:53]
	v_mfma_f32_16x16x32_bf16 v[46:49], v[198:201], v[182:185], v[46:49]
	v_mfma_f32_16x16x32_bf16 v[42:45], v[206:209], v[182:185], v[42:45]
	v_mfma_f32_16x16x32_bf16 v[38:41], v[198:201], v[190:193], v[38:41]
	v_mfma_f32_16x16x32_bf16 v[34:37], v[206:209], v[190:193], v[34:37]
	s_barrier
	ds_read_b128 v[162:165], v156 offset:49152
	ds_read_b128 v[166:169], v156 offset:50176
	ds_read_b128 v[170:173], v156 offset:51200
	ds_read_b128 v[174:177], v156 offset:52224
	ds_read_b128 v[178:181], v156 offset:53248
	ds_read_b128 v[182:185], v156 offset:54272
	ds_read_b128 v[186:189], v156 offset:55296
	ds_read_b128 v[190:193], v156 offset:56320
	s_add_i32 s0, s0, s5
	v_lshl_add_u64 v[214:215], v[210:211], 0, s[38:39]
	s_mov_b32 m0, s0
	s_nop 0
	global_load_lds_dwordx4 v[214:215], off
	v_lshl_add_u64 v[214:215], v[210:211], 0, s[42:43]
	s_add_i32 m0, s0, 0x2000
	s_nop 0
	global_load_lds_dwordx4 v[214:215], off
	s_add_i32 s0, s1, s5
	v_lshl_add_u64 v[250:251], v[210:211], 0, s[44:45]
	s_mov_b32 m0, s0
	s_nop 0
	global_load_lds_dwordx4 v[250:251], off
	v_lshl_add_u64 v[250:251], v[210:211], 0, s[46:47]
	s_add_i32 m0, s0, 0x2000
	s_nop 0
	global_load_lds_dwordx4 v[250:251], off
	s_mov_b32 m0, s37
	v_lshl_add_u64 v[214:215], v[212:213], 0, s[38:39]
	global_load_lds_dwordx4 v[214:215], off
	v_lshl_add_u64 v[212:213], v[212:213], 0, s[42:43]
	s_mov_b32 m0, s40
	s_nop 0
	global_load_lds_dwordx4 v[212:213], off
	s_waitcnt vmcnt(8)
	s_waitcnt lgkmcnt(0)
	s_barrier
	v_mfma_f32_16x16x32_bf16 v[94:97], v[130:133], v[162:165], v[94:97]
	v_mfma_f32_16x16x32_bf16 v[90:93], v[148:151], v[162:165], v[90:93]
	v_mfma_f32_16x16x32_bf16 v[86:89], v[130:133], v[170:173], v[86:89]
	v_mfma_f32_16x16x32_bf16 v[82:85], v[148:151], v[170:173], v[82:85]
	v_mfma_f32_16x16x32_bf16 v[78:81], v[130:133], v[178:181], v[78:81]
	v_mfma_f32_16x16x32_bf16 v[74:77], v[148:151], v[178:181], v[74:77]
	v_mfma_f32_16x16x32_bf16 v[70:73], v[130:133], v[186:189], v[70:73]
	v_mfma_f32_16x16x32_bf16 v[66:69], v[148:151], v[186:189], v[66:69]
	v_mfma_f32_16x16x32_bf16 v[94:97], v[134:137], v[166:169], v[94:97]
	v_mfma_f32_16x16x32_bf16 v[90:93], v[158:161], v[166:169], v[90:93]
	v_mfma_f32_16x16x32_bf16 v[86:89], v[134:137], v[174:177], v[86:89]
	v_mfma_f32_16x16x32_bf16 v[82:85], v[158:161], v[174:177], v[82:85]
	v_mfma_f32_16x16x32_bf16 v[78:81], v[134:137], v[182:185], v[78:81]
	v_mfma_f32_16x16x32_bf16 v[74:77], v[158:161], v[182:185], v[74:77]
	v_mfma_f32_16x16x32_bf16 v[70:73], v[134:137], v[190:193], v[70:73]
	v_mfma_f32_16x16x32_bf16 v[66:69], v[158:161], v[190:193], v[66:69]
	v_mfma_f32_16x16x32_bf16 v[30:33], v[194:197], v[162:165], v[30:33]
	v_mfma_f32_16x16x32_bf16 v[26:29], v[202:205], v[162:165], v[26:29]
	v_mfma_f32_16x16x32_bf16 v[22:25], v[194:197], v[170:173], v[22:25]
	v_mfma_f32_16x16x32_bf16 v[18:21], v[202:205], v[170:173], v[18:21]
	v_mfma_f32_16x16x32_bf16 v[14:17], v[194:197], v[178:181], v[14:17]
	v_mfma_f32_16x16x32_bf16 v[10:13], v[202:205], v[178:181], v[10:13]
	v_mfma_f32_16x16x32_bf16 v[6:9], v[194:197], v[186:189], v[6:9]
	v_mfma_f32_16x16x32_bf16 v[2:5], v[202:205], v[186:189], v[2:5]
	v_mfma_f32_16x16x32_bf16 v[30:33], v[198:201], v[166:169], v[30:33]
	v_mfma_f32_16x16x32_bf16 v[26:29], v[206:209], v[166:169], v[26:29]
	v_mfma_f32_16x16x32_bf16 v[22:25], v[198:201], v[174:177], v[22:25]
	v_mfma_f32_16x16x32_bf16 v[18:21], v[206:209], v[174:177], v[18:21]
	v_mfma_f32_16x16x32_bf16 v[14:17], v[198:201], v[182:185], v[14:17]
	v_mfma_f32_16x16x32_bf16 v[10:13], v[206:209], v[182:185], v[10:13]
	v_mfma_f32_16x16x32_bf16 v[6:9], v[198:201], v[190:193], v[6:9]
	v_mfma_f32_16x16x32_bf16 v[2:5], v[206:209], v[190:193], v[2:5]
	s_add_i32 s68, s68, 2
	s_add_u32 s66, s66, 0x100
	s_addc_u32 s67, s67, 0
	s_add_u32 s64, s64, 0x100
	s_addc_u32 s65, s65, 0
	s_cmp_gt_u32 s68, 13
	s_barrier
	s_cbranch_scc0 .LBB0_190
	s_setprio 0
	s_mov_b32 s98, 1
	s_and_b64 vcc, exec, s[48:49]
	s_cbranch_vccz .LBB0_193
	s_barrier

.LBB0_1048:
	s_add_u32 s38, s68, 0x100
	s_addc_u32 s68, s69, 0
	s_add_u32 s66, s66, 0x40080
	v_mov_b32_e32 v2, 0
	s_addc_u32 s67, s67, 0
	s_mov_b32 s69, -2
	v_mov_b32_e32 v3, 0
	v_pk_mov_b32 v[4:5], v[2:3], v[2:3]
	v_pk_mov_b32 v[6:7], v[2:3], v[2:3]
	v_pk_mov_b32 v[8:9], v[2:3], v[2:3]
	v_pk_mov_b32 v[10:11], v[2:3], v[2:3]
	v_pk_mov_b32 v[12:13], v[2:3], v[2:3]
	v_pk_mov_b32 v[14:15], v[2:3], v[2:3]
	v_pk_mov_b32 v[16:17], v[2:3], v[2:3]
	v_pk_mov_b32 v[18:19], v[2:3], v[2:3]
	v_pk_mov_b32 v[20:21], v[2:3], v[2:3]
	v_pk_mov_b32 v[22:23], v[2:3], v[2:3]
	v_pk_mov_b32 v[24:25], v[2:3], v[2:3]
	v_pk_mov_b32 v[26:27], v[2:3], v[2:3]
	v_pk_mov_b32 v[28:29], v[2:3], v[2:3]
	v_pk_mov_b32 v[30:31], v[2:3], v[2:3]
	v_pk_mov_b32 v[32:33], v[2:3], v[2:3]
	v_pk_mov_b32 v[34:35], v[2:3], v[2:3]
	v_pk_mov_b32 v[36:37], v[2:3], v[2:3]
	v_pk_mov_b32 v[38:39], v[2:3], v[2:3]
	v_pk_mov_b32 v[40:41], v[2:3], v[2:3]
	v_pk_mov_b32 v[42:43], v[2:3], v[2:3]
	v_pk_mov_b32 v[44:45], v[2:3], v[2:3]
	v_pk_mov_b32 v[46:47], v[2:3], v[2:3]
	v_pk_mov_b32 v[48:49], v[2:3], v[2:3]
	v_pk_mov_b32 v[50:51], v[2:3], v[2:3]
	v_pk_mov_b32 v[52:53], v[2:3], v[2:3]
	v_pk_mov_b32 v[54:55], v[2:3], v[2:3]
	v_pk_mov_b32 v[56:57], v[2:3], v[2:3]
	v_pk_mov_b32 v[58:59], v[2:3], v[2:3]
	v_pk_mov_b32 v[60:61], v[2:3], v[2:3]
	v_pk_mov_b32 v[62:63], v[2:3], v[2:3]
	v_pk_mov_b32 v[64:65], v[2:3], v[2:3]
	v_pk_mov_b32 v[66:67], v[2:3], v[2:3]
	v_pk_mov_b32 v[68:69], v[2:3], v[2:3]
	v_pk_mov_b32 v[70:71], v[2:3], v[2:3]
	v_pk_mov_b32 v[72:73], v[2:3], v[2:3]
	v_pk_mov_b32 v[74:75], v[2:3], v[2:3]
	v_pk_mov_b32 v[76:77], v[2:3], v[2:3]
	v_pk_mov_b32 v[78:79], v[2:3], v[2:3]
	v_pk_mov_b32 v[80:81], v[2:3], v[2:3]
	v_pk_mov_b32 v[82:83], v[2:3], v[2:3]
	v_pk_mov_b32 v[84:85], v[2:3], v[2:3]
	v_pk_mov_b32 v[86:87], v[2:3], v[2:3]
	v_pk_mov_b32 v[88:89], v[2:3], v[2:3]
	v_pk_mov_b32 v[90:91], v[2:3], v[2:3]
	v_pk_mov_b32 v[92:93], v[2:3], v[2:3]
	v_pk_mov_b32 v[94:95], v[2:3], v[2:3]
	v_pk_mov_b32 v[96:97], v[2:3], v[2:3]
	v_pk_mov_b32 v[98:99], v[2:3], v[2:3]
	v_pk_mov_b32 v[100:101], v[2:3], v[2:3]
	v_pk_mov_b32 v[102:103], v[2:3], v[2:3]
	v_pk_mov_b32 v[104:105], v[2:3], v[2:3]
	v_pk_mov_b32 v[106:107], v[2:3], v[2:3]
	v_pk_mov_b32 v[108:109], v[2:3], v[2:3]
	v_pk_mov_b32 v[110:111], v[2:3], v[2:3]
	v_pk_mov_b32 v[112:113], v[2:3], v[2:3]
	v_pk_mov_b32 v[114:115], v[2:3], v[2:3]
	v_pk_mov_b32 v[116:117], v[2:3], v[2:3]
	v_pk_mov_b32 v[118:119], v[2:3], v[2:3]
	v_pk_mov_b32 v[120:121], v[2:3], v[2:3]
	v_pk_mov_b32 v[122:123], v[2:3], v[2:3]
	v_pk_mov_b32 v[124:125], v[2:3], v[2:3]
	v_pk_mov_b32 v[126:127], v[2:3], v[2:3]
	v_pk_mov_b32 v[128:129], v[2:3], v[2:3]
	v_readfirstlane_b32 s100, v0
	s_bitcmp1_b32 s100, 8
	s_cbranch_scc0 .Lsp_p7
	s_setprio 1
.Lsp_p7:
.LBB0_1049:
	ds_read_b128 v[130:133], v155
	ds_read_b128 v[134:137], v155 offset:1024
	ds_read_b128 v[148:151], v155 offset:2048
	ds_read_b128 v[158:161], v155 offset:3072
	ds_read_b128 v[194:197], v157
	ds_read_b128 v[198:201], v157 offset:1024
	ds_read_b128 v[202:205], v157 offset:2048
	ds_read_b128 v[206:209], v157 offset:3072
	s_add_u32 s0, s66, 0xfffc0080
	s_addc_u32 s1, s67, -1
	s_cmp_eq_u32 s69, 12
	s_cselect_b32 s1, s13, s1
	s_cselect_b32 s0, s12, s0
	s_cselect_b32 s31, s65, s68
	s_cselect_b32 s30, s64, s38
	v_lshl_add_u64 v[252:253], s[66:67], 0, v[142:143]
	s_add_i32 m0, s9, 0xc000
	ds_read_b128 v[162:165], v156
	ds_read_b128 v[166:169], v156 offset:1024
	ds_read_b128 v[170:173], v156 offset:2048
	ds_read_b128 v[174:177], v156 offset:3072
	ds_read_b128 v[178:181], v156 offset:4096
	ds_read_b128 v[182:185], v156 offset:5120
	ds_read_b128 v[186:189], v156 offset:6144
	ds_read_b128 v[190:193], v156 offset:7168
	global_load_lds_dwordx4 v[252:253], off
	v_lshl_add_u64 v[252:253], v[252:253], 0, s[14:15]
	s_add_i32 m0, s9, 0xe000
	s_nop 0
	global_load_lds_dwordx4 v[252:253], off
	s_cmp_lg_u32 s98, 0
	s_cbranch_scc1 .Lsk1_p7
	s_waitcnt vmcnt(8)

.Lsk3_p7:
	s_waitcnt lgkmcnt(0)
	s_barrier
	v_mfma_f32_16x16x32_bf16 v[94:97], v[130:133], v[162:165], v[94:97]
	v_mfma_f32_16x16x32_bf16 v[90:93], v[148:151], v[162:165], v[90:93]
	v_mfma_f32_16x16x32_bf16 v[86:89], v[130:133], v[170:173], v[86:89]
	v_mfma_f32_16x16x32_bf16 v[82:85], v[148:151], v[170:173], v[82:85]
	v_mfma_f32_16x16x32_bf16 v[78:81], v[130:133], v[178:181], v[78:81]
	v_mfma_f32_16x16x32_bf16 v[74:77], v[148:151], v[178:181], v[74:77]
	v_mfma_f32_16x16x32_bf16 v[70:73], v[130:133], v[186:189], v[70:73]
	v_mfma_f32_16x16x32_bf16 v[66:69], v[148:151], v[186:189], v[66:69]
	v_mfma_f32_16x16x32_bf16 v[94:97], v[134:137], v[166:169], v[94:97]
	v_mfma_f32_16x16x32_bf16 v[90:93], v[158:161], v[166:169], v[90:93]
	v_mfma_f32_16x16x32_bf16 v[86:89], v[134:137], v[174:177], v[86:89]
	v_mfma_f32_16x16x32_bf16 v[82:85], v[158:161], v[174:177], v[82:85]
	v_mfma_f32_16x16x32_bf16 v[78:81], v[134:137], v[182:185], v[78:81]
	v_mfma_f32_16x16x32_bf16 v[74:77], v[158:161], v[182:185], v[74:77]
	v_mfma_f32_16x16x32_bf16 v[70:73], v[134:137], v[190:193], v[70:73]
	v_mfma_f32_16x16x32_bf16 v[66:69], v[158:161], v[190:193], v[66:69]
	v_mfma_f32_16x16x32_bf16 v[30:33], v[194:197], v[162:165], v[30:33]
	v_mfma_f32_16x16x32_bf16 v[26:29], v[202:205], v[162:165], v[26:29]
	v_mfma_f32_16x16x32_bf16 v[22:25], v[194:197], v[170:173], v[22:25]
	v_mfma_f32_16x16x32_bf16 v[18:21], v[202:205], v[170:173], v[18:21]
	v_mfma_f32_16x16x32_bf16 v[14:17], v[194:197], v[178:181], v[14:17]
	v_mfma_f32_16x16x32_bf16 v[10:13], v[202:205], v[178:181], v[10:13]
	v_mfma_f32_16x16x32_bf16 v[6:9], v[194:197], v[186:189], v[6:9]
	v_mfma_f32_16x16x32_bf16 v[2:5], v[202:205], v[186:189], v[2:5]
	v_mfma_f32_16x16x32_bf16 v[30:33], v[198:201], v[166:169], v[30:33]
	v_mfma_f32_16x16x32_bf16 v[26:29], v[206:209], v[166:169], v[26:29]
	v_mfma_f32_16x16x32_bf16 v[22:25], v[198:201], v[174:177], v[22:25]
	v_mfma_f32_16x16x32_bf16 v[18:21], v[206:209], v[174:177], v[18:21]
	v_mfma_f32_16x16x32_bf16 v[14:17], v[198:201], v[182:185], v[14:17]
	v_mfma_f32_16x16x32_bf16 v[10:13], v[206:209], v[182:185], v[10:13]
	v_mfma_f32_16x16x32_bf16 v[6:9], v[198:201], v[190:193], v[6:9]
	v_mfma_f32_16x16x32_bf16 v[2:5], v[206:209], v[190:193], v[2:5]
	s_add_i32 s0, 0, 0x18000
	v_add_u32_e32 v158, s0, v154
	s_barrier
	s_add_i32 s1, 0, 0x1c000
	v_add_u32_e32 v206, s1, v154
	ds_read_b128 v[130:133], v158
	ds_read_b128 v[134:137], v158 offset:1024
	ds_read_b128 v[148:151], v158 offset:2048
	ds_read_b128 v[158:161], v158 offset:3072
	ds_read_b128 v[194:197], v206
	ds_read_b128 v[198:201], v206 offset:1024
	ds_read_b128 v[202:205], v206 offset:2048
	ds_read_b128 v[206:209], v206 offset:3072
	s_mov_b32 m0, s25
	v_lshl_add_u64 v[252:253], v[212:213], 0, s[18:19]
	ds_read_b128 v[162:165], v156 offset:32768
	ds_read_b128 v[166:169], v156 offset:33792
	ds_read_b128 v[170:173], v156 offset:34816
	ds_read_b128 v[174:177], v156 offset:35840
	ds_read_b128 v[178:181], v156 offset:36864
	ds_read_b128 v[182:185], v156 offset:37888
	ds_read_b128 v[186:189], v156 offset:38912
	ds_read_b128 v[190:193], v156 offset:39936
	global_load_lds_dwordx4 v[252:253], off
	v_lshl_add_u64 v[252:253], v[212:213], 0, s[20:21]
	s_mov_b32 m0, s26
	s_nop 0
	global_load_lds_dwordx4 v[252:253], off
	s_waitcnt vmcnt(8)
	s_waitcnt lgkmcnt(0)
	s_barrier
	v_mfma_f32_16x16x32_bf16 v[126:129], v[130:133], v[162:165], v[126:129]
	v_mfma_f32_16x16x32_bf16 v[122:125], v[148:151], v[162:165], v[122:125]
	v_mfma_f32_16x16x32_bf16 v[118:121], v[130:133], v[170:173], v[118:121]
	v_mfma_f32_16x16x32_bf16 v[114:117], v[148:151], v[170:173], v[114:117]
	v_mfma_f32_16x16x32_bf16 v[110:113], v[130:133], v[178:181], v[110:113]
	v_mfma_f32_16x16x32_bf16 v[106:109], v[148:151], v[178:181], v[106:109]
	v_mfma_f32_16x16x32_bf16 v[102:105], v[130:133], v[186:189], v[102:105]
	v_mfma_f32_16x16x32_bf16 v[98:101], v[148:151], v[186:189], v[98:101]
	v_mfma_f32_16x16x32_bf16 v[126:129], v[134:137], v[166:169], v[126:129]
	v_mfma_f32_16x16x32_bf16 v[122:125], v[158:161], v[166:169], v[122:125]
	v_mfma_f32_16x16x32_bf16 v[118:121], v[134:137], v[174:177], v[118:121]
	v_mfma_f32_16x16x32_bf16 v[114:117], v[158:161], v[174:177], v[114:117]
	v_mfma_f32_16x16x32_bf16 v[110:113], v[134:137], v[182:185], v[110:113]
	v_mfma_f32_16x16x32_bf16 v[106:109], v[158:161], v[182:185], v[106:109]
	v_mfma_f32_16x16x32_bf16 v[102:105], v[134:137], v[190:193], v[102:105]
	v_mfma_f32_16x16x32_bf16 v[98:101], v[158:161], v[190:193], v[98:101]
	v_mfma_f32_16x16x32_bf16 v[62:65], v[194:197], v[162:165], v[62:65]
	v_mfma_f32_16x16x32_bf16 v[58:61], v[202:205], v[162:165], v[58:61]
	v_mfma_f32_16x16x32_bf16 v[54:57], v[194:197], v[170:173], v[54:57]
	v_mfma_f32_16x16x32_bf16 v[50:53], v[202:205], v[170:173], v[50:53]
	v_mfma_f32_16x16x32_bf16 v[46:49], v[194:197], v[178:181], v[46:49]
	v_mfma_f32_16x16x32_bf16 v[42:45], v[202:205], v[178:181], v[42:45]
	v_mfma_f32_16x16x32_bf16 v[38:41], v[194:197], v[186:189], v[38:41]
	v_mfma_f32_16x16x32_bf16 v[34:37], v[202:205], v[186:189], v[34:37]
	v_mfma_f32_16x16x32_bf16 v[62:65], v[198:201], v[166:169], v[62:65]
	v_mfma_f32_16x16x32_bf16 v[58:61], v[206:209], v[166:169], v[58:61]
	v_mfma_f32_16x16x32_bf16 v[54:57], v[198:201], v[174:177], v[54:57]
	v_mfma_f32_16x16x32_bf16 v[50:53], v[206:209], v[174:177], v[50:53]
	v_mfma_f32_16x16x32_bf16 v[46:49], v[198:201], v[182:185], v[46:49]
	v_mfma_f32_16x16x32_bf16 v[42:45], v[206:209], v[182:185], v[42:45]
	v_mfma_f32_16x16x32_bf16 v[38:41], v[198:201], v[190:193], v[38:41]
	v_mfma_f32_16x16x32_bf16 v[34:37], v[206:209], v[190:193], v[34:37]
	s_barrier
	ds_read_b128 v[162:165], v156 offset:49152
	ds_read_b128 v[166:169], v156 offset:50176
	ds_read_b128 v[170:173], v156 offset:51200
	ds_read_b128 v[174:177], v156 offset:52224
	ds_read_b128 v[178:181], v156 offset:53248
	ds_read_b128 v[182:185], v156 offset:54272
	ds_read_b128 v[186:189], v156 offset:55296
	ds_read_b128 v[190:193], v156 offset:56320
	s_add_i32 s0, s0, s7
	v_lshl_add_u64 v[214:215], v[210:211], 0, s[42:43]
	s_mov_b32 m0, s0
	s_nop 0
	global_load_lds_dwordx4 v[214:215], off
	v_lshl_add_u64 v[214:215], v[210:211], 0, s[44:45]
	s_add_i32 m0, s0, 0x2000
	s_nop 0
	global_load_lds_dwordx4 v[214:215], off
	s_add_i32 s0, s1, s7
	v_lshl_add_u64 v[250:251], v[210:211], 0, s[46:47]
	s_mov_b32 m0, s0
	s_nop 0
	global_load_lds_dwordx4 v[250:251], off
	v_lshl_add_u64 v[250:251], v[210:211], 0, s[48:49]
	s_add_i32 m0, s0, 0x2000
	s_nop 0
	global_load_lds_dwordx4 v[250:251], off
	s_mov_b32 m0, s72
	v_lshl_add_u64 v[214:215], v[212:213], 0, s[42:43]
	global_load_lds_dwordx4 v[214:215], off
	v_lshl_add_u64 v[212:213], v[212:213], 0, s[44:45]
	s_mov_b32 m0, s73
	s_nop 0
	global_load_lds_dwordx4 v[212:213], off
	s_waitcnt vmcnt(8)
	s_waitcnt lgkmcnt(0)
	s_barrier
	v_mfma_f32_16x16x32_bf16 v[94:97], v[130:133], v[162:165], v[94:97]
	v_mfma_f32_16x16x32_bf16 v[90:93], v[148:151], v[162:165], v[90:93]
	v_mfma_f32_16x16x32_bf16 v[86:89], v[130:133], v[170:173], v[86:89]
	v_mfma_f32_16x16x32_bf16 v[82:85], v[148:151], v[170:173], v[82:85]
	v_mfma_f32_16x16x32_bf16 v[78:81], v[130:133], v[178:181], v[78:81]
	v_mfma_f32_16x16x32_bf16 v[74:77], v[148:151], v[178:181], v[74:77]
	v_mfma_f32_16x16x32_bf16 v[70:73], v[130:133], v[186:189], v[70:73]
	v_mfma_f32_16x16x32_bf16 v[66:69], v[148:151], v[186:189], v[66:69]
	v_mfma_f32_16x16x32_bf16 v[94:97], v[134:137], v[166:169], v[94:97]
	v_mfma_f32_16x16x32_bf16 v[90:93], v[158:161], v[166:169], v[90:93]
	v_mfma_f32_16x16x32_bf16 v[86:89], v[134:137], v[174:177], v[86:89]
	v_mfma_f32_16x16x32_bf16 v[82:85], v[158:161], v[174:177], v[82:85]
	v_mfma_f32_16x16x32_bf16 v[78:81], v[134:137], v[182:185], v[78:81]
	v_mfma_f32_16x16x32_bf16 v[74:77], v[158:161], v[182:185], v[74:77]
	v_mfma_f32_16x16x32_bf16 v[70:73], v[134:137], v[190:193], v[70:73]
	v_mfma_f32_16x16x32_bf16 v[66:69], v[158:161], v[190:193], v[66:69]
	v_mfma_f32_16x16x32_bf16 v[30:33], v[194:197], v[162:165], v[30:33]
	v_mfma_f32_16x16x32_bf16 v[26:29], v[202:205], v[162:165], v[26:29]
	v_mfma_f32_16x16x32_bf16 v[22:25], v[194:197], v[170:173], v[22:25]
	v_mfma_f32_16x16x32_bf16 v[18:21], v[202:205], v[170:173], v[18:21]
	v_mfma_f32_16x16x32_bf16 v[14:17], v[194:197], v[178:181], v[14:17]
	v_mfma_f32_16x16x32_bf16 v[10:13], v[202:205], v[178:181], v[10:13]
	v_mfma_f32_16x16x32_bf16 v[6:9], v[194:197], v[186:189], v[6:9]
	v_mfma_f32_16x16x32_bf16 v[2:5], v[202:205], v[186:189], v[2:5]
	v_mfma_f32_16x16x32_bf16 v[30:33], v[198:201], v[166:169], v[30:33]
	v_mfma_f32_16x16x32_bf16 v[26:29], v[206:209], v[166:169], v[26:29]
	v_mfma_f32_16x16x32_bf16 v[22:25], v[198:201], v[174:177], v[22:25]
	v_mfma_f32_16x16x32_bf16 v[18:21], v[206:209], v[174:177], v[18:21]
	v_mfma_f32_16x16x32_bf16 v[14:17], v[198:201], v[182:185], v[14:17]
	v_mfma_f32_16x16x32_bf16 v[10:13], v[206:209], v[182:185], v[10:13]
	v_mfma_f32_16x16x32_bf16 v[6:9], v[198:201], v[190:193], v[6:9]
	v_mfma_f32_16x16x32_bf16 v[2:5], v[206:209], v[190:193], v[2:5]
	s_add_i32 s69, s69, 2
	s_add_u32 s38, s38, 0x100
	s_addc_u32 s68, s68, 0
	s_add_u32 s66, s66, 0x100
	s_addc_u32 s67, s67, 0
	s_cmp_gt_u32 s69, 13
	s_barrier
	s_cbranch_scc0 .LBB0_1049
	s_setprio 0
	s_mov_b32 s98, 1
	s_and_b64 vcc, exec, s[50:51]
	s_cbranch_vccz .LBB0_1052
	s_barrier

.LBB0_1630:
	s_add_u32 s62, s62, 0x100
	s_addc_u32 s63, s63, 0
	s_add_u32 s60, s60, 0x40080
	v_mov_b32_e32 v2, 0
	s_addc_u32 s61, s61, 0
	s_mov_b32 s79, -2
	v_mov_b32_e32 v3, 0
	v_pk_mov_b32 v[4:5], v[2:3], v[2:3]
	v_pk_mov_b32 v[6:7], v[2:3], v[2:3]
	v_pk_mov_b32 v[8:9], v[2:3], v[2:3]
	v_pk_mov_b32 v[10:11], v[2:3], v[2:3]
	v_pk_mov_b32 v[12:13], v[2:3], v[2:3]
	v_pk_mov_b32 v[14:15], v[2:3], v[2:3]
	v_pk_mov_b32 v[16:17], v[2:3], v[2:3]
	v_pk_mov_b32 v[18:19], v[2:3], v[2:3]
	v_pk_mov_b32 v[20:21], v[2:3], v[2:3]
	v_pk_mov_b32 v[22:23], v[2:3], v[2:3]
	v_pk_mov_b32 v[24:25], v[2:3], v[2:3]
	v_pk_mov_b32 v[26:27], v[2:3], v[2:3]
	v_pk_mov_b32 v[28:29], v[2:3], v[2:3]
	v_pk_mov_b32 v[30:31], v[2:3], v[2:3]
	v_pk_mov_b32 v[32:33], v[2:3], v[2:3]
	v_pk_mov_b32 v[34:35], v[2:3], v[2:3]
	v_pk_mov_b32 v[36:37], v[2:3], v[2:3]
	v_pk_mov_b32 v[38:39], v[2:3], v[2:3]
	v_pk_mov_b32 v[40:41], v[2:3], v[2:3]
	v_pk_mov_b32 v[42:43], v[2:3], v[2:3]
	v_pk_mov_b32 v[44:45], v[2:3], v[2:3]
	v_pk_mov_b32 v[46:47], v[2:3], v[2:3]
	v_pk_mov_b32 v[48:49], v[2:3], v[2:3]
	v_pk_mov_b32 v[50:51], v[2:3], v[2:3]
	v_pk_mov_b32 v[52:53], v[2:3], v[2:3]
	v_pk_mov_b32 v[54:55], v[2:3], v[2:3]
	v_pk_mov_b32 v[56:57], v[2:3], v[2:3]
	v_pk_mov_b32 v[58:59], v[2:3], v[2:3]
	v_pk_mov_b32 v[60:61], v[2:3], v[2:3]
	v_pk_mov_b32 v[62:63], v[2:3], v[2:3]
	v_pk_mov_b32 v[64:65], v[2:3], v[2:3]
	v_pk_mov_b32 v[66:67], v[2:3], v[2:3]
	v_pk_mov_b32 v[68:69], v[2:3], v[2:3]
	v_pk_mov_b32 v[70:71], v[2:3], v[2:3]
	v_pk_mov_b32 v[72:73], v[2:3], v[2:3]
	v_pk_mov_b32 v[74:75], v[2:3], v[2:3]
	v_pk_mov_b32 v[76:77], v[2:3], v[2:3]
	v_pk_mov_b32 v[78:79], v[2:3], v[2:3]
	v_pk_mov_b32 v[80:81], v[2:3], v[2:3]
	v_pk_mov_b32 v[82:83], v[2:3], v[2:3]
	v_pk_mov_b32 v[84:85], v[2:3], v[2:3]
	v_pk_mov_b32 v[86:87], v[2:3], v[2:3]
	v_pk_mov_b32 v[88:89], v[2:3], v[2:3]
	v_pk_mov_b32 v[90:91], v[2:3], v[2:3]
	v_pk_mov_b32 v[92:93], v[2:3], v[2:3]
	v_pk_mov_b32 v[94:95], v[2:3], v[2:3]
	v_pk_mov_b32 v[96:97], v[2:3], v[2:3]
	v_pk_mov_b32 v[98:99], v[2:3], v[2:3]
	v_pk_mov_b32 v[100:101], v[2:3], v[2:3]
	v_pk_mov_b32 v[102:103], v[2:3], v[2:3]
	v_pk_mov_b32 v[104:105], v[2:3], v[2:3]
	v_pk_mov_b32 v[106:107], v[2:3], v[2:3]
	v_pk_mov_b32 v[108:109], v[2:3], v[2:3]
	v_pk_mov_b32 v[110:111], v[2:3], v[2:3]
	v_pk_mov_b32 v[112:113], v[2:3], v[2:3]
	v_pk_mov_b32 v[114:115], v[2:3], v[2:3]
	v_pk_mov_b32 v[116:117], v[2:3], v[2:3]
	v_pk_mov_b32 v[118:119], v[2:3], v[2:3]
	v_pk_mov_b32 v[120:121], v[2:3], v[2:3]
	v_pk_mov_b32 v[126:127], v[2:3], v[2:3]
	v_pk_mov_b32 v[128:129], v[2:3], v[2:3]
	v_pk_mov_b32 v[130:131], v[2:3], v[2:3]
	v_pk_mov_b32 v[132:133], v[2:3], v[2:3]
	v_readfirstlane_b32 s100, v0
	s_bitcmp1_b32 s100, 8
	s_cbranch_scc0 .Lsp_p13
	s_setprio 1
.Lsp_p13:
.LBB0_1631:
	ds_read_b128 v[122:125], v189
	ds_read_b128 v[134:137], v189 offset:1024
	ds_read_b128 v[138:141], v189 offset:2048
	ds_read_b128 v[142:145], v189 offset:3072
	ds_read_b128 v[192:195], v191
	ds_read_b128 v[196:199], v191 offset:1024
	ds_read_b128 v[200:203], v191 offset:2048
	ds_read_b128 v[204:207], v191 offset:3072
	s_add_u32 s0, s60, 0xfffc0080
	s_addc_u32 s1, s61, -1
	s_cmp_eq_u32 s79, 12
	s_cselect_b32 s1, s57, s1
	s_cselect_b32 s0, s56, s0
	s_cselect_b32 s31, s59, s63
	s_cselect_b32 s30, s58, s62
	v_lshl_add_u64 v[252:253], s[60:61], 0, v[166:167]
	s_add_i32 m0, s6, 0xc000
	ds_read_b128 v[146:149], v190
	ds_read_b128 v[150:153], v190 offset:1024
	ds_read_b128 v[154:157], v190 offset:2048
	ds_read_b128 v[158:161], v190 offset:3072
	ds_read_b128 v[168:171], v190 offset:4096
	ds_read_b128 v[172:175], v190 offset:5120
	ds_read_b128 v[176:179], v190 offset:6144
	ds_read_b128 v[180:183], v190 offset:7168
	global_load_lds_dwordx4 v[252:253], off
	v_lshl_add_u64 v[252:253], v[252:253], 0, s[12:13]
	s_add_i32 m0, s6, 0xe000
	s_nop 0
	global_load_lds_dwordx4 v[252:253], off
	s_cmp_lg_u32 s98, 0
	s_cbranch_scc1 .Lsk1_p13
	s_waitcnt vmcnt(8)

.Lsk3_p13:
	s_waitcnt lgkmcnt(0)
	s_barrier
	v_mfma_f32_16x16x32_bf16 v[94:97], v[122:125], v[146:149], v[94:97]
	v_mfma_f32_16x16x32_bf16 v[90:93], v[138:141], v[146:149], v[90:93]
	v_mfma_f32_16x16x32_bf16 v[86:89], v[122:125], v[154:157], v[86:89]
	v_mfma_f32_16x16x32_bf16 v[82:85], v[138:141], v[154:157], v[82:85]
	v_mfma_f32_16x16x32_bf16 v[78:81], v[122:125], v[168:171], v[78:81]
	v_mfma_f32_16x16x32_bf16 v[74:77], v[138:141], v[168:171], v[74:77]
	v_mfma_f32_16x16x32_bf16 v[70:73], v[122:125], v[176:179], v[70:73]
	v_mfma_f32_16x16x32_bf16 v[66:69], v[138:141], v[176:179], v[66:69]
	v_mfma_f32_16x16x32_bf16 v[94:97], v[134:137], v[150:153], v[94:97]
	v_mfma_f32_16x16x32_bf16 v[90:93], v[142:145], v[150:153], v[90:93]
	v_mfma_f32_16x16x32_bf16 v[86:89], v[134:137], v[158:161], v[86:89]
	v_mfma_f32_16x16x32_bf16 v[82:85], v[142:145], v[158:161], v[82:85]
	v_mfma_f32_16x16x32_bf16 v[78:81], v[134:137], v[172:175], v[78:81]
	v_mfma_f32_16x16x32_bf16 v[74:77], v[142:145], v[172:175], v[74:77]
	v_mfma_f32_16x16x32_bf16 v[70:73], v[134:137], v[180:183], v[70:73]
	v_mfma_f32_16x16x32_bf16 v[66:69], v[142:145], v[180:183], v[66:69]
	v_mfma_f32_16x16x32_bf16 v[30:33], v[192:195], v[146:149], v[30:33]
	v_mfma_f32_16x16x32_bf16 v[26:29], v[200:203], v[146:149], v[26:29]
	v_mfma_f32_16x16x32_bf16 v[22:25], v[192:195], v[154:157], v[22:25]
	v_mfma_f32_16x16x32_bf16 v[18:21], v[200:203], v[154:157], v[18:21]
	v_mfma_f32_16x16x32_bf16 v[14:17], v[192:195], v[168:171], v[14:17]
	v_mfma_f32_16x16x32_bf16 v[10:13], v[200:203], v[168:171], v[10:13]
	v_mfma_f32_16x16x32_bf16 v[6:9], v[192:195], v[176:179], v[6:9]
	v_mfma_f32_16x16x32_bf16 v[2:5], v[200:203], v[176:179], v[2:5]
	v_mfma_f32_16x16x32_bf16 v[30:33], v[196:199], v[150:153], v[30:33]
	v_mfma_f32_16x16x32_bf16 v[26:29], v[204:207], v[150:153], v[26:29]
	v_mfma_f32_16x16x32_bf16 v[22:25], v[196:199], v[158:161], v[22:25]
	v_mfma_f32_16x16x32_bf16 v[18:21], v[204:207], v[158:161], v[18:21]
	v_mfma_f32_16x16x32_bf16 v[14:17], v[196:199], v[172:175], v[14:17]
	v_mfma_f32_16x16x32_bf16 v[10:13], v[204:207], v[172:175], v[10:13]
	v_mfma_f32_16x16x32_bf16 v[6:9], v[196:199], v[180:183], v[6:9]
	v_mfma_f32_16x16x32_bf16 v[2:5], v[204:207], v[180:183], v[2:5]
	s_add_i32 s0, 0, 0x18000
	v_add_u32_e32 v142, s0, v188
	s_barrier
	s_add_i32 s1, 0, 0x1c000
	v_add_u32_e32 v204, s1, v188
	ds_read_b128 v[122:125], v142
	ds_read_b128 v[134:137], v142 offset:1024
	ds_read_b128 v[138:141], v142 offset:2048
	ds_read_b128 v[142:145], v142 offset:3072
	ds_read_b128 v[192:195], v204
	ds_read_b128 v[196:199], v204 offset:1024
	ds_read_b128 v[200:203], v204 offset:2048
	ds_read_b128 v[204:207], v204 offset:3072
	s_mov_b32 m0, s24
	v_lshl_add_u64 v[252:253], v[208:209], 0, s[14:15]
	ds_read_b128 v[146:149], v190 offset:32768
	ds_read_b128 v[150:153], v190 offset:33792
	ds_read_b128 v[154:157], v190 offset:34816
	ds_read_b128 v[158:161], v190 offset:35840
	ds_read_b128 v[168:171], v190 offset:36864
	ds_read_b128 v[172:175], v190 offset:37888
	ds_read_b128 v[176:179], v190 offset:38912
	ds_read_b128 v[180:183], v190 offset:39936
	global_load_lds_dwordx4 v[252:253], off
	v_lshl_add_u64 v[252:253], v[208:209], 0, s[16:17]
	s_mov_b32 m0, s25
	s_nop 0
	global_load_lds_dwordx4 v[252:253], off
	s_waitcnt vmcnt(8)
	s_waitcnt lgkmcnt(0)
	s_barrier
	v_mfma_f32_16x16x32_bf16 v[130:133], v[122:125], v[146:149], v[130:133]
	v_mfma_f32_16x16x32_bf16 v[126:129], v[138:141], v[146:149], v[126:129]
	v_mfma_f32_16x16x32_bf16 v[118:121], v[122:125], v[154:157], v[118:121]
	v_mfma_f32_16x16x32_bf16 v[114:117], v[138:141], v[154:157], v[114:117]
	v_mfma_f32_16x16x32_bf16 v[110:113], v[122:125], v[168:171], v[110:113]
	v_mfma_f32_16x16x32_bf16 v[106:109], v[138:141], v[168:171], v[106:109]
	v_mfma_f32_16x16x32_bf16 v[102:105], v[122:125], v[176:179], v[102:105]
	v_mfma_f32_16x16x32_bf16 v[98:101], v[138:141], v[176:179], v[98:101]
	v_mfma_f32_16x16x32_bf16 v[130:133], v[134:137], v[150:153], v[130:133]
	v_mfma_f32_16x16x32_bf16 v[126:129], v[142:145], v[150:153], v[126:129]
	v_mfma_f32_16x16x32_bf16 v[118:121], v[134:137], v[158:161], v[118:121]
	v_mfma_f32_16x16x32_bf16 v[114:117], v[142:145], v[158:161], v[114:117]
	v_mfma_f32_16x16x32_bf16 v[110:113], v[134:137], v[172:175], v[110:113]
	v_mfma_f32_16x16x32_bf16 v[106:109], v[142:145], v[172:175], v[106:109]
	v_mfma_f32_16x16x32_bf16 v[102:105], v[134:137], v[180:183], v[102:105]
	v_mfma_f32_16x16x32_bf16 v[98:101], v[142:145], v[180:183], v[98:101]
	v_mfma_f32_16x16x32_bf16 v[62:65], v[192:195], v[146:149], v[62:65]
	v_mfma_f32_16x16x32_bf16 v[58:61], v[200:203], v[146:149], v[58:61]
	v_mfma_f32_16x16x32_bf16 v[54:57], v[192:195], v[154:157], v[54:57]
	v_mfma_f32_16x16x32_bf16 v[50:53], v[200:203], v[154:157], v[50:53]
	v_mfma_f32_16x16x32_bf16 v[46:49], v[192:195], v[168:171], v[46:49]
	v_mfma_f32_16x16x32_bf16 v[42:45], v[200:203], v[168:171], v[42:45]
	v_mfma_f32_16x16x32_bf16 v[38:41], v[192:195], v[176:179], v[38:41]
	v_mfma_f32_16x16x32_bf16 v[34:37], v[200:203], v[176:179], v[34:37]
	v_mfma_f32_16x16x32_bf16 v[62:65], v[196:199], v[150:153], v[62:65]
	v_mfma_f32_16x16x32_bf16 v[58:61], v[204:207], v[150:153], v[58:61]
	v_mfma_f32_16x16x32_bf16 v[54:57], v[196:199], v[158:161], v[54:57]
	v_mfma_f32_16x16x32_bf16 v[50:53], v[204:207], v[158:161], v[50:53]
	v_mfma_f32_16x16x32_bf16 v[46:49], v[196:199], v[172:175], v[46:49]
	v_mfma_f32_16x16x32_bf16 v[42:45], v[204:207], v[172:175], v[42:45]
	v_mfma_f32_16x16x32_bf16 v[38:41], v[196:199], v[180:183], v[38:41]
	v_mfma_f32_16x16x32_bf16 v[34:37], v[204:207], v[180:183], v[34:37]
	s_barrier
	ds_read_b128 v[146:149], v190 offset:49152
	ds_read_b128 v[150:153], v190 offset:50176
	ds_read_b128 v[154:157], v190 offset:51200
	ds_read_b128 v[158:161], v190 offset:52224
	ds_read_b128 v[168:171], v190 offset:53248
	ds_read_b128 v[172:175], v190 offset:54272
	ds_read_b128 v[176:179], v190 offset:55296
	ds_read_b128 v[180:183], v190 offset:56320
	s_add_i32 s0, s0, s5
	v_lshl_add_u64 v[210:211], v[184:185], 0, s[22:23]
	s_mov_b32 m0, s0
	s_nop 0
	global_load_lds_dwordx4 v[210:211], off
	v_lshl_add_u64 v[210:211], v[184:185], 0, s[34:35]
	s_add_i32 m0, s0, 0x2000
	s_nop 0
	global_load_lds_dwordx4 v[210:211], off
	s_add_i32 s0, s1, s5
	v_lshl_add_u64 v[250:251], v[184:185], 0, s[36:37]
	s_mov_b32 m0, s0
	s_nop 0
	global_load_lds_dwordx4 v[250:251], off
	v_lshl_add_u64 v[250:251], v[184:185], 0, s[38:39]
	s_add_i32 m0, s0, 0x2000
	s_nop 0
	global_load_lds_dwordx4 v[250:251], off
	s_mov_b32 m0, s66
	v_lshl_add_u64 v[210:211], v[208:209], 0, s[22:23]
	global_load_lds_dwordx4 v[210:211], off
	v_lshl_add_u64 v[208:209], v[208:209], 0, s[34:35]
	s_mov_b32 m0, s67
	s_nop 0
	global_load_lds_dwordx4 v[208:209], off
	s_waitcnt vmcnt(8)
	s_waitcnt lgkmcnt(0)
	s_barrier
	v_mfma_f32_16x16x32_bf16 v[94:97], v[122:125], v[146:149], v[94:97]
	v_mfma_f32_16x16x32_bf16 v[90:93], v[138:141], v[146:149], v[90:93]
	v_mfma_f32_16x16x32_bf16 v[86:89], v[122:125], v[154:157], v[86:89]
	v_mfma_f32_16x16x32_bf16 v[82:85], v[138:141], v[154:157], v[82:85]
	v_mfma_f32_16x16x32_bf16 v[78:81], v[122:125], v[168:171], v[78:81]
	v_mfma_f32_16x16x32_bf16 v[74:77], v[138:141], v[168:171], v[74:77]
	v_mfma_f32_16x16x32_bf16 v[70:73], v[122:125], v[176:179], v[70:73]
	v_mfma_f32_16x16x32_bf16 v[66:69], v[138:141], v[176:179], v[66:69]
	v_mfma_f32_16x16x32_bf16 v[94:97], v[134:137], v[150:153], v[94:97]
	v_mfma_f32_16x16x32_bf16 v[90:93], v[142:145], v[150:153], v[90:93]
	v_mfma_f32_16x16x32_bf16 v[86:89], v[134:137], v[158:161], v[86:89]
	v_mfma_f32_16x16x32_bf16 v[82:85], v[142:145], v[158:161], v[82:85]
	v_mfma_f32_16x16x32_bf16 v[78:81], v[134:137], v[172:175], v[78:81]
	v_mfma_f32_16x16x32_bf16 v[74:77], v[142:145], v[172:175], v[74:77]
	v_mfma_f32_16x16x32_bf16 v[70:73], v[134:137], v[180:183], v[70:73]
	v_mfma_f32_16x16x32_bf16 v[66:69], v[142:145], v[180:183], v[66:69]
	v_mfma_f32_16x16x32_bf16 v[30:33], v[192:195], v[146:149], v[30:33]
	v_mfma_f32_16x16x32_bf16 v[26:29], v[200:203], v[146:149], v[26:29]
	v_mfma_f32_16x16x32_bf16 v[22:25], v[192:195], v[154:157], v[22:25]
	v_mfma_f32_16x16x32_bf16 v[18:21], v[200:203], v[154:157], v[18:21]
	v_mfma_f32_16x16x32_bf16 v[14:17], v[192:195], v[168:171], v[14:17]
	v_mfma_f32_16x16x32_bf16 v[10:13], v[200:203], v[168:171], v[10:13]
	v_mfma_f32_16x16x32_bf16 v[6:9], v[192:195], v[176:179], v[6:9]
	v_mfma_f32_16x16x32_bf16 v[2:5], v[200:203], v[176:179], v[2:5]
	v_mfma_f32_16x16x32_bf16 v[30:33], v[196:199], v[150:153], v[30:33]
	v_mfma_f32_16x16x32_bf16 v[26:29], v[204:207], v[150:153], v[26:29]
	v_mfma_f32_16x16x32_bf16 v[22:25], v[196:199], v[158:161], v[22:25]
	v_mfma_f32_16x16x32_bf16 v[18:21], v[204:207], v[158:161], v[18:21]
	v_mfma_f32_16x16x32_bf16 v[14:17], v[196:199], v[172:175], v[14:17]
	v_mfma_f32_16x16x32_bf16 v[10:13], v[204:207], v[172:175], v[10:13]
	v_mfma_f32_16x16x32_bf16 v[6:9], v[196:199], v[180:183], v[6:9]
	v_mfma_f32_16x16x32_bf16 v[2:5], v[204:207], v[180:183], v[2:5]
	s_add_i32 s79, s79, 2
	s_add_u32 s62, s62, 0x100
	s_addc_u32 s63, s63, 0
	s_add_u32 s60, s60, 0x100
	s_addc_u32 s61, s61, 0
	s_cmp_gt_u32 s79, 13
	s_barrier
	s_cbranch_scc0 .LBB0_1631
	s_setprio 0
	s_mov_b32 s98, 1
	s_and_b64 vcc, exec, s[40:41]
	s_cbranch_vccz .LBB0_1634
	s_barrier

.LBB0_1705:
	s_add_u32 s62, s62, 0x100
	s_addc_u32 s63, s63, 0
	s_add_u32 s60, s60, 0x40080
	v_mov_b32_e32 v2, 0
	s_addc_u32 s61, s61, 0
	s_mov_b32 s86, -2
	v_mov_b32_e32 v3, 0
	v_pk_mov_b32 v[4:5], v[2:3], v[2:3]
	v_pk_mov_b32 v[6:7], v[2:3], v[2:3]
	v_pk_mov_b32 v[8:9], v[2:3], v[2:3]
	v_pk_mov_b32 v[10:11], v[2:3], v[2:3]
	v_pk_mov_b32 v[12:13], v[2:3], v[2:3]
	v_pk_mov_b32 v[14:15], v[2:3], v[2:3]
	v_pk_mov_b32 v[16:17], v[2:3], v[2:3]
	v_pk_mov_b32 v[18:19], v[2:3], v[2:3]
	v_pk_mov_b32 v[20:21], v[2:3], v[2:3]
	v_pk_mov_b32 v[22:23], v[2:3], v[2:3]
	v_pk_mov_b32 v[24:25], v[2:3], v[2:3]
	v_pk_mov_b32 v[26:27], v[2:3], v[2:3]
	v_pk_mov_b32 v[28:29], v[2:3], v[2:3]
	v_pk_mov_b32 v[30:31], v[2:3], v[2:3]
	v_pk_mov_b32 v[32:33], v[2:3], v[2:3]
	v_pk_mov_b32 v[34:35], v[2:3], v[2:3]
	v_pk_mov_b32 v[36:37], v[2:3], v[2:3]
	v_pk_mov_b32 v[38:39], v[2:3], v[2:3]
	v_pk_mov_b32 v[40:41], v[2:3], v[2:3]
	v_pk_mov_b32 v[42:43], v[2:3], v[2:3]
	v_pk_mov_b32 v[44:45], v[2:3], v[2:3]
	v_pk_mov_b32 v[46:47], v[2:3], v[2:3]
	v_pk_mov_b32 v[48:49], v[2:3], v[2:3]
	v_pk_mov_b32 v[50:51], v[2:3], v[2:3]
	v_pk_mov_b32 v[52:53], v[2:3], v[2:3]
	v_pk_mov_b32 v[54:55], v[2:3], v[2:3]
	v_pk_mov_b32 v[56:57], v[2:3], v[2:3]
	v_pk_mov_b32 v[58:59], v[2:3], v[2:3]
	v_pk_mov_b32 v[60:61], v[2:3], v[2:3]
	v_pk_mov_b32 v[62:63], v[2:3], v[2:3]
	v_pk_mov_b32 v[64:65], v[2:3], v[2:3]
	v_pk_mov_b32 v[66:67], v[2:3], v[2:3]
	v_pk_mov_b32 v[68:69], v[2:3], v[2:3]
	v_pk_mov_b32 v[70:71], v[2:3], v[2:3]
	v_pk_mov_b32 v[72:73], v[2:3], v[2:3]
	v_pk_mov_b32 v[74:75], v[2:3], v[2:3]
	v_pk_mov_b32 v[76:77], v[2:3], v[2:3]
	v_pk_mov_b32 v[78:79], v[2:3], v[2:3]
	v_pk_mov_b32 v[80:81], v[2:3], v[2:3]
	v_pk_mov_b32 v[82:83], v[2:3], v[2:3]
	v_pk_mov_b32 v[84:85], v[2:3], v[2:3]
	v_pk_mov_b32 v[86:87], v[2:3], v[2:3]
	v_pk_mov_b32 v[88:89], v[2:3], v[2:3]
	v_pk_mov_b32 v[90:91], v[2:3], v[2:3]
	v_pk_mov_b32 v[92:93], v[2:3], v[2:3]
	v_pk_mov_b32 v[94:95], v[2:3], v[2:3]
	v_pk_mov_b32 v[96:97], v[2:3], v[2:3]
	v_pk_mov_b32 v[98:99], v[2:3], v[2:3]
	v_pk_mov_b32 v[100:101], v[2:3], v[2:3]
	v_pk_mov_b32 v[102:103], v[2:3], v[2:3]
	v_pk_mov_b32 v[104:105], v[2:3], v[2:3]
	v_pk_mov_b32 v[106:107], v[2:3], v[2:3]
	v_pk_mov_b32 v[108:109], v[2:3], v[2:3]
	v_pk_mov_b32 v[110:111], v[2:3], v[2:3]
	v_pk_mov_b32 v[112:113], v[2:3], v[2:3]
	v_pk_mov_b32 v[114:115], v[2:3], v[2:3]
	v_pk_mov_b32 v[116:117], v[2:3], v[2:3]
	v_pk_mov_b32 v[118:119], v[2:3], v[2:3]
	v_pk_mov_b32 v[120:121], v[2:3], v[2:3]
	v_pk_mov_b32 v[122:123], v[2:3], v[2:3]
	v_pk_mov_b32 v[124:125], v[2:3], v[2:3]
	v_pk_mov_b32 v[126:127], v[2:3], v[2:3]
	v_pk_mov_b32 v[128:129], v[2:3], v[2:3]
	v_readfirstlane_b32 s100, v0
	s_bitcmp1_b32 s100, 8
	s_cbranch_scc0 .Lsp_p14
	s_setprio 1
.Lsp_p14:
.LBB0_1706:
	ds_read_b128 v[130:133], v213
	ds_read_b128 v[134:137], v213 offset:1024
	ds_read_b128 v[138:141], v213 offset:2048
	ds_read_b128 v[142:145], v213 offset:3072
	ds_read_b128 v[178:181], v215
	ds_read_b128 v[182:185], v215 offset:1024
	ds_read_b128 v[186:189], v215 offset:2048
	ds_read_b128 v[190:193], v215 offset:3072
	s_add_u32 s0, s60, 0xfffc0080
	s_addc_u32 s1, s61, -1
	s_cmp_eq_u32 s86, 12
	s_cselect_b32 s1, s9, s1
	s_cselect_b32 s0, s8, s0
	s_cselect_b32 s31, s59, s63
	s_cselect_b32 s30, s58, s62
	v_lshl_add_u64 v[252:253], s[60:61], 0, v[198:199]
	s_add_i32 m0, s6, 0xc000
	ds_read_b128 v[146:149], v214
	ds_read_b128 v[150:153], v214 offset:1024
	ds_read_b128 v[154:157], v214 offset:2048
	ds_read_b128 v[158:161], v214 offset:3072
	ds_read_b128 v[162:165], v214 offset:4096
	ds_read_b128 v[166:169], v214 offset:5120
	ds_read_b128 v[170:173], v214 offset:6144
	ds_read_b128 v[174:177], v214 offset:7168
	global_load_lds_dwordx4 v[252:253], off
	v_lshl_add_u64 v[252:253], v[252:253], 0, s[10:11]
	s_add_i32 m0, s6, 0xe000
	s_nop 0
	global_load_lds_dwordx4 v[252:253], off
	s_cmp_lg_u32 s98, 0
	s_cbranch_scc1 .Lsk1_p14
	s_waitcnt vmcnt(8)

.Lsk3_p14:
	s_waitcnt lgkmcnt(0)
	s_barrier
	v_mfma_f32_16x16x32_bf16 v[94:97], v[130:133], v[146:149], v[94:97]
	v_mfma_f32_16x16x32_bf16 v[90:93], v[138:141], v[146:149], v[90:93]
	v_mfma_f32_16x16x32_bf16 v[86:89], v[130:133], v[154:157], v[86:89]
	v_mfma_f32_16x16x32_bf16 v[82:85], v[138:141], v[154:157], v[82:85]
	v_mfma_f32_16x16x32_bf16 v[78:81], v[130:133], v[162:165], v[78:81]
	v_mfma_f32_16x16x32_bf16 v[74:77], v[138:141], v[162:165], v[74:77]
	v_mfma_f32_16x16x32_bf16 v[70:73], v[130:133], v[170:173], v[70:73]
	v_mfma_f32_16x16x32_bf16 v[66:69], v[138:141], v[170:173], v[66:69]
	v_mfma_f32_16x16x32_bf16 v[94:97], v[134:137], v[150:153], v[94:97]
	v_mfma_f32_16x16x32_bf16 v[90:93], v[142:145], v[150:153], v[90:93]
	v_mfma_f32_16x16x32_bf16 v[86:89], v[134:137], v[158:161], v[86:89]
	v_mfma_f32_16x16x32_bf16 v[82:85], v[142:145], v[158:161], v[82:85]
	v_mfma_f32_16x16x32_bf16 v[78:81], v[134:137], v[166:169], v[78:81]
	v_mfma_f32_16x16x32_bf16 v[74:77], v[142:145], v[166:169], v[74:77]
	v_mfma_f32_16x16x32_bf16 v[70:73], v[134:137], v[174:177], v[70:73]
	v_mfma_f32_16x16x32_bf16 v[66:69], v[142:145], v[174:177], v[66:69]
	v_mfma_f32_16x16x32_bf16 v[30:33], v[178:181], v[146:149], v[30:33]
	v_mfma_f32_16x16x32_bf16 v[26:29], v[186:189], v[146:149], v[26:29]
	v_mfma_f32_16x16x32_bf16 v[22:25], v[178:181], v[154:157], v[22:25]
	v_mfma_f32_16x16x32_bf16 v[18:21], v[186:189], v[154:157], v[18:21]
	v_mfma_f32_16x16x32_bf16 v[14:17], v[178:181], v[162:165], v[14:17]
	v_mfma_f32_16x16x32_bf16 v[10:13], v[186:189], v[162:165], v[10:13]
	v_mfma_f32_16x16x32_bf16 v[6:9], v[178:181], v[170:173], v[6:9]
	v_mfma_f32_16x16x32_bf16 v[2:5], v[186:189], v[170:173], v[2:5]
	v_mfma_f32_16x16x32_bf16 v[30:33], v[182:185], v[150:153], v[30:33]
	v_mfma_f32_16x16x32_bf16 v[26:29], v[190:193], v[150:153], v[26:29]
	v_mfma_f32_16x16x32_bf16 v[22:25], v[182:185], v[158:161], v[22:25]
	v_mfma_f32_16x16x32_bf16 v[18:21], v[190:193], v[158:161], v[18:21]
	v_mfma_f32_16x16x32_bf16 v[14:17], v[182:185], v[166:169], v[14:17]
	v_mfma_f32_16x16x32_bf16 v[10:13], v[190:193], v[166:169], v[10:13]
	v_mfma_f32_16x16x32_bf16 v[6:9], v[182:185], v[174:177], v[6:9]
	v_mfma_f32_16x16x32_bf16 v[2:5], v[190:193], v[174:177], v[2:5]
	s_add_i32 s0, 0, 0x18000
	v_add_u32_e32 v142, s0, v212
	s_barrier
	s_add_i32 s1, 0, 0x1c000
	v_add_u32_e32 v190, s1, v212
	ds_read_b128 v[130:133], v142
	ds_read_b128 v[134:137], v142 offset:1024
	ds_read_b128 v[138:141], v142 offset:2048
	ds_read_b128 v[142:145], v142 offset:3072
	ds_read_b128 v[178:181], v190
	ds_read_b128 v[182:185], v190 offset:1024
	ds_read_b128 v[186:189], v190 offset:2048
	ds_read_b128 v[190:193], v190 offset:3072
	s_mov_b32 m0, s24
	v_lshl_add_u64 v[252:253], v[202:203], 0, s[16:17]
	ds_read_b128 v[146:149], v214 offset:32768
	ds_read_b128 v[150:153], v214 offset:33792
	ds_read_b128 v[154:157], v214 offset:34816
	ds_read_b128 v[158:161], v214 offset:35840
	ds_read_b128 v[162:165], v214 offset:36864
	ds_read_b128 v[166:169], v214 offset:37888
	ds_read_b128 v[170:173], v214 offset:38912
	ds_read_b128 v[174:177], v214 offset:39936
	global_load_lds_dwordx4 v[252:253], off
	v_lshl_add_u64 v[252:253], v[202:203], 0, s[18:19]
	s_mov_b32 m0, s25
	s_nop 0
	global_load_lds_dwordx4 v[252:253], off
	s_waitcnt vmcnt(8)
	s_waitcnt lgkmcnt(0)
	s_barrier
	v_mfma_f32_16x16x32_bf16 v[126:129], v[130:133], v[146:149], v[126:129]
	v_mfma_f32_16x16x32_bf16 v[122:125], v[138:141], v[146:149], v[122:125]
	v_mfma_f32_16x16x32_bf16 v[118:121], v[130:133], v[154:157], v[118:121]
	v_mfma_f32_16x16x32_bf16 v[114:117], v[138:141], v[154:157], v[114:117]
	v_mfma_f32_16x16x32_bf16 v[110:113], v[130:133], v[162:165], v[110:113]
	v_mfma_f32_16x16x32_bf16 v[106:109], v[138:141], v[162:165], v[106:109]
	v_mfma_f32_16x16x32_bf16 v[102:105], v[130:133], v[170:173], v[102:105]
	v_mfma_f32_16x16x32_bf16 v[98:101], v[138:141], v[170:173], v[98:101]
	v_mfma_f32_16x16x32_bf16 v[126:129], v[134:137], v[150:153], v[126:129]
	v_mfma_f32_16x16x32_bf16 v[122:125], v[142:145], v[150:153], v[122:125]
	v_mfma_f32_16x16x32_bf16 v[118:121], v[134:137], v[158:161], v[118:121]
	v_mfma_f32_16x16x32_bf16 v[114:117], v[142:145], v[158:161], v[114:117]
	v_mfma_f32_16x16x32_bf16 v[110:113], v[134:137], v[166:169], v[110:113]
	v_mfma_f32_16x16x32_bf16 v[106:109], v[142:145], v[166:169], v[106:109]
	v_mfma_f32_16x16x32_bf16 v[102:105], v[134:137], v[174:177], v[102:105]
	v_mfma_f32_16x16x32_bf16 v[98:101], v[142:145], v[174:177], v[98:101]
	v_mfma_f32_16x16x32_bf16 v[62:65], v[178:181], v[146:149], v[62:65]
	v_mfma_f32_16x16x32_bf16 v[58:61], v[186:189], v[146:149], v[58:61]
	v_mfma_f32_16x16x32_bf16 v[54:57], v[178:181], v[154:157], v[54:57]
	v_mfma_f32_16x16x32_bf16 v[50:53], v[186:189], v[154:157], v[50:53]
	v_mfma_f32_16x16x32_bf16 v[46:49], v[178:181], v[162:165], v[46:49]
	v_mfma_f32_16x16x32_bf16 v[42:45], v[186:189], v[162:165], v[42:45]
	v_mfma_f32_16x16x32_bf16 v[38:41], v[178:181], v[170:173], v[38:41]
	v_mfma_f32_16x16x32_bf16 v[34:37], v[186:189], v[170:173], v[34:37]
	v_mfma_f32_16x16x32_bf16 v[62:65], v[182:185], v[150:153], v[62:65]
	v_mfma_f32_16x16x32_bf16 v[58:61], v[190:193], v[150:153], v[58:61]
	v_mfma_f32_16x16x32_bf16 v[54:57], v[182:185], v[158:161], v[54:57]
	v_mfma_f32_16x16x32_bf16 v[50:53], v[190:193], v[158:161], v[50:53]
	v_mfma_f32_16x16x32_bf16 v[46:49], v[182:185], v[166:169], v[46:49]
	v_mfma_f32_16x16x32_bf16 v[42:45], v[190:193], v[166:169], v[42:45]
	v_mfma_f32_16x16x32_bf16 v[38:41], v[182:185], v[174:177], v[38:41]
	v_mfma_f32_16x16x32_bf16 v[34:37], v[190:193], v[174:177], v[34:37]
	s_barrier
	ds_read_b128 v[146:149], v214 offset:49152
	ds_read_b128 v[150:153], v214 offset:50176
	ds_read_b128 v[154:157], v214 offset:51200
	ds_read_b128 v[158:161], v214 offset:52224
	ds_read_b128 v[162:165], v214 offset:53248
	ds_read_b128 v[166:169], v214 offset:54272
	ds_read_b128 v[170:173], v214 offset:55296
	ds_read_b128 v[174:177], v214 offset:56320
	s_add_i32 s0, s0, s5
	v_lshl_add_u64 v[204:205], v[200:201], 0, s[38:39]
	s_mov_b32 m0, s0
	s_nop 0
	global_load_lds_dwordx4 v[204:205], off
	v_lshl_add_u64 v[204:205], v[200:201], 0, s[40:41]
	s_add_i32 m0, s0, 0x2000
	s_nop 0
	global_load_lds_dwordx4 v[204:205], off
	s_add_i32 s0, s1, s5
	v_lshl_add_u64 v[250:251], v[200:201], 0, s[42:43]
	s_mov_b32 m0, s0
	s_nop 0
	global_load_lds_dwordx4 v[250:251], off
	v_lshl_add_u64 v[250:251], v[200:201], 0, s[44:45]
	s_add_i32 m0, s0, 0x2000
	s_nop 0
	global_load_lds_dwordx4 v[250:251], off
	s_mov_b32 m0, s65
	v_lshl_add_u64 v[204:205], v[202:203], 0, s[38:39]
	global_load_lds_dwordx4 v[204:205], off
	v_lshl_add_u64 v[202:203], v[202:203], 0, s[40:41]
	s_mov_b32 m0, s66
	s_nop 0
	global_load_lds_dwordx4 v[202:203], off
	s_waitcnt vmcnt(8)
	s_waitcnt lgkmcnt(0)
	s_barrier
	v_mfma_f32_16x16x32_bf16 v[94:97], v[130:133], v[146:149], v[94:97]
	v_mfma_f32_16x16x32_bf16 v[90:93], v[138:141], v[146:149], v[90:93]
	v_mfma_f32_16x16x32_bf16 v[86:89], v[130:133], v[154:157], v[86:89]
	v_mfma_f32_16x16x32_bf16 v[82:85], v[138:141], v[154:157], v[82:85]
	v_mfma_f32_16x16x32_bf16 v[78:81], v[130:133], v[162:165], v[78:81]
	v_mfma_f32_16x16x32_bf16 v[74:77], v[138:141], v[162:165], v[74:77]
	v_mfma_f32_16x16x32_bf16 v[70:73], v[130:133], v[170:173], v[70:73]
	v_mfma_f32_16x16x32_bf16 v[66:69], v[138:141], v[170:173], v[66:69]
	v_mfma_f32_16x16x32_bf16 v[94:97], v[134:137], v[150:153], v[94:97]
	v_mfma_f32_16x16x32_bf16 v[90:93], v[142:145], v[150:153], v[90:93]
	v_mfma_f32_16x16x32_bf16 v[86:89], v[134:137], v[158:161], v[86:89]
	v_mfma_f32_16x16x32_bf16 v[82:85], v[142:145], v[158:161], v[82:85]
	v_mfma_f32_16x16x32_bf16 v[78:81], v[134:137], v[166:169], v[78:81]
	v_mfma_f32_16x16x32_bf16 v[74:77], v[142:145], v[166:169], v[74:77]
	v_mfma_f32_16x16x32_bf16 v[70:73], v[134:137], v[174:177], v[70:73]
	v_mfma_f32_16x16x32_bf16 v[66:69], v[142:145], v[174:177], v[66:69]
	v_mfma_f32_16x16x32_bf16 v[30:33], v[178:181], v[146:149], v[30:33]
	v_mfma_f32_16x16x32_bf16 v[26:29], v[186:189], v[146:149], v[26:29]
	v_mfma_f32_16x16x32_bf16 v[22:25], v[178:181], v[154:157], v[22:25]
	v_mfma_f32_16x16x32_bf16 v[18:21], v[186:189], v[154:157], v[18:21]
	v_mfma_f32_16x16x32_bf16 v[14:17], v[178:181], v[162:165], v[14:17]
	v_mfma_f32_16x16x32_bf16 v[10:13], v[186:189], v[162:165], v[10:13]
	v_mfma_f32_16x16x32_bf16 v[6:9], v[178:181], v[170:173], v[6:9]
	v_mfma_f32_16x16x32_bf16 v[2:5], v[186:189], v[170:173], v[2:5]
	v_mfma_f32_16x16x32_bf16 v[30:33], v[182:185], v[150:153], v[30:33]
	v_mfma_f32_16x16x32_bf16 v[26:29], v[190:193], v[150:153], v[26:29]
	v_mfma_f32_16x16x32_bf16 v[22:25], v[182:185], v[158:161], v[22:25]
	v_mfma_f32_16x16x32_bf16 v[18:21], v[190:193], v[158:161], v[18:21]
	v_mfma_f32_16x16x32_bf16 v[14:17], v[182:185], v[166:169], v[14:17]
	v_mfma_f32_16x16x32_bf16 v[10:13], v[190:193], v[166:169], v[10:13]
	v_mfma_f32_16x16x32_bf16 v[6:9], v[182:185], v[174:177], v[6:9]
	v_mfma_f32_16x16x32_bf16 v[2:5], v[190:193], v[174:177], v[2:5]
	s_add_i32 s86, s86, 2
	s_add_u32 s62, s62, 0x100
	s_addc_u32 s63, s63, 0
	s_add_u32 s60, s60, 0x100
	s_addc_u32 s61, s61, 0
	s_cmp_gt_u32 s86, 13
	s_barrier
	s_cbranch_scc0 .LBB0_1706
	s_setprio 0
	s_mov_b32 s98, 1
	s_and_b64 vcc, exec, s[46:47]
	s_cbranch_vccz .LBB0_1709
	s_barrier
